# MFMA issue order inside every 32-MFMA block of the three GEMM K-loops changed to k-innermost (both k-steps of an accumulator back to back); row-statistics loads hoisted
# speedup vs baseline: 1.0117x; 1.0117x over previous
; #define PG8_STAGE(bufoff, gbase, voff) do { _Pragma("unroll") for (int _i = 0; _i < 2; ++_i) \
;         __builtin_amdgcn_global_load_lds((const unsigned*)((const char*)(gbase) + (voff)[_i]), (PG8_LAS unsigned*)(lds + (bufoff) + ldsw + _i * 8192), 16, 0, 0); } while (0)
; #define PG8_LDA(dst, b, h) do { _Pragma("unroll") for (int m = 0; m < 4; ++m) _Pragma("unroll") for (int k = 0; k < 2; ++k) dst[m][k] = *(const PG8_LAS bf16x8*)(lds + PG8_SA(b, h) + aoff + m * 2048 + k * 1024); } while (0)
; #define PG8_LDB(dst, b, h) do { _Pragma("unroll") for (int n = 0; n < 2; ++n) _Pragma("unroll") for (int k = 0; k < 2; ++k) dst[n][k] = *(const PG8_LAS bf16x8*)(lds + PG8_SB(b, h) + boff + n * 2048 + k * 1024); } while (0)
; #define PG8_MMA(ai, bj, At, Bt) do { __builtin_amdgcn_s_setprio(1); _Pragma("unroll") for (int m = 0; m < 4; ++m) _Pragma("unroll") for (int n = 0; n < 2; ++n) _Pragma("unroll") for (int k = 0; k < 2; ++k) \
;         acc[ai][bj][m][n] = __builtin_amdgcn_mfma_f32_16x16x32_bf16(Bt[n][k], At[m][k], acc[ai][bj][m][n], 0, 0, 0); __builtin_amdgcn_s_setprio(0); } while (0)
; #define PG8_WAIT_V(n) asm volatile("s_waitcnt vmcnt(" #n ")" ::: "memory")
; #define PG8_WAIT_L(n) asm volatile("s_waitcnt lgkmcnt(" #n ")" ::: "memory")
; template <class Epi, class Sched, bool ALIGN_EPI = false, bool SP2 = false>
; __device__ __forceinline__ void gemm_phase(PG8_LAS unsigned char* lds, const Gemm g, const Sched& S, const Epi& E, const int tid_in) {
;     ...
;             const bool last = (t == nt - 2);
;             const char* a1 = cA + (size_t)(t + 1) * kstep;
;             const char* a2 = last ? nA : cA + (size_t)(t + 2) * kstep; const char* b2 = last ? nB : cB + (size_t)(t + 2) * kstep;
;             const char* a3 = a2 + kstep; const char* b3 = b2 + kstep;
;             if (last && has_next) S.a_ready(nxt);
;             if constexpr (SP2) {
;             PG8_LDB(B0, 0, 0); PG8_LDB(B1, 0, 1); PG8_SCHED; PG8_LDA(At, 0, 0); PG8_STAGE(PG8_SA(1, 1), a1 + hstep, voffA);
;             PG8_WAIT_V(8); PG8_WAIT_L(0); PG8_BAR; PG8_MMA(0, 0, At, B0); PG8_MMA(0, 1, At, B1); PG8_BAR; PG8_SCHED;
;             PG8_LDA(At, 0, 1); PG8_STAGE(PG8_SB(0, 0), b2, voffB); PG8_STAGE(PG8_SB(0, 1), b2 + hstep, voffB); PG8_STAGE(PG8_SA(0, 0), a2, voffA);
;             PG8_WAIT_V(8); PG8_WAIT_L(0); PG8_BAR; PG8_MMA(1, 0, At, B0); PG8_MMA(1, 1, At, B1); PG8_BAR; PG8_SCHED;
.LBB0_93:
	s_add_u32 s12, s42, 0xfffc0080
	s_addc_u32 s13, s43, -1
	s_add_i32 s46, 0, 0x10000
	s_cmp_eq_u32 s45, 12
	s_cselect_b32 s15, s11, s13
	s_cselect_b32 s14, s16, s12
	v_add_u32_e32 v148, s46, v150
	s_cselect_b32 s13, s17, s39
	s_cselect_b32 s12, s21, s25
	s_add_i32 s48, 0, 0x14000
	ds_read_b128 v[144:147], v148
	ds_read_b128 v[154:157], v148 offset:1024
	ds_read_b128 v[158:161], v148 offset:2048
	ds_read_b128 v[162:165], v148 offset:3072
	v_add_u32_e32 v148, s48, v150
	ds_read_b128 v[166:169], v148
	ds_read_b128 v[170:173], v148 offset:1024
	ds_read_b128 v[174:177], v148 offset:2048
	ds_read_b128 v[178:181], v148 offset:3072
	v_lshl_add_u64 v[148:149], s[42:43], 0, v[140:141]
	s_add_i32 m0, s22, 0xc000
	ds_read_b128 v[182:185], v152
	ds_read_b128 v[186:189], v152 offset:1024
	ds_read_b128 v[190:193], v152 offset:2048
	ds_read_b128 v[198:201], v152 offset:3072
	ds_read_b128 v[202:205], v152 offset:4096
	ds_read_b128 v[206:209], v152 offset:5120
	ds_read_b128 v[210:213], v152 offset:6144
	ds_read_b128 v[214:217], v152 offset:7168
	global_load_lds_dwordx4 v[148:149], off
	v_lshl_add_u64 v[148:149], s[42:43], 0, v[142:143]
	s_add_i32 m0, s22, 0xe000
	s_nop 0
	global_load_lds_dwordx4 v[148:149], off
	s_waitcnt vmcnt(8)
	s_waitcnt lgkmcnt(0)
	s_barrier
	s_setprio 1
	s_waitcnt lgkmcnt(0)
	v_mfma_f32_16x16x32_bf16 v[130:133], v[144:147], v[182:185], v[130:133]
	v_mfma_f32_16x16x32_bf16 v[130:133], v[154:157], v[186:189], v[130:133]
	v_mfma_f32_16x16x32_bf16 v[114:117], v[144:147], v[190:193], v[114:117]
	v_mfma_f32_16x16x32_bf16 v[114:117], v[154:157], v[198:201], v[114:117]
	v_mfma_f32_16x16x32_bf16 v[98:101], v[144:147], v[202:205], v[98:101]
	v_mfma_f32_16x16x32_bf16 v[98:101], v[154:157], v[206:209], v[98:101]
	v_mfma_f32_16x16x32_bf16 v[82:85], v[144:147], v[210:213], v[82:85]
	v_mfma_f32_16x16x32_bf16 v[82:85], v[154:157], v[214:217], v[82:85]
	v_mfma_f32_16x16x32_bf16 v[126:129], v[158:161], v[182:185], v[126:129]
	v_mfma_f32_16x16x32_bf16 v[126:129], v[162:165], v[186:189], v[126:129]
	v_mfma_f32_16x16x32_bf16 v[110:113], v[158:161], v[190:193], v[110:113]
	v_mfma_f32_16x16x32_bf16 v[110:113], v[162:165], v[198:201], v[110:113]
	v_mfma_f32_16x16x32_bf16 v[94:97], v[158:161], v[202:205], v[94:97]
	v_mfma_f32_16x16x32_bf16 v[94:97], v[162:165], v[206:209], v[94:97]
	v_mfma_f32_16x16x32_bf16 v[78:81], v[158:161], v[210:213], v[78:81]
	v_mfma_f32_16x16x32_bf16 v[78:81], v[162:165], v[214:217], v[78:81]
	v_mfma_f32_16x16x32_bf16 v[122:125], v[166:169], v[182:185], v[122:125]
	v_mfma_f32_16x16x32_bf16 v[122:125], v[170:173], v[186:189], v[122:125]
	v_mfma_f32_16x16x32_bf16 v[106:109], v[166:169], v[190:193], v[106:109]
	v_mfma_f32_16x16x32_bf16 v[106:109], v[170:173], v[198:201], v[106:109]
	v_mfma_f32_16x16x32_bf16 v[90:93], v[166:169], v[202:205], v[90:93]
	v_mfma_f32_16x16x32_bf16 v[90:93], v[170:173], v[206:209], v[90:93]
	v_mfma_f32_16x16x32_bf16 v[74:77], v[166:169], v[210:213], v[74:77]
	v_mfma_f32_16x16x32_bf16 v[74:77], v[170:173], v[214:217], v[74:77]
	v_mfma_f32_16x16x32_bf16 v[118:121], v[174:177], v[182:185], v[118:121]
	v_mfma_f32_16x16x32_bf16 v[118:121], v[178:181], v[186:189], v[118:121]
	v_mfma_f32_16x16x32_bf16 v[102:105], v[174:177], v[190:193], v[102:105]
	v_mfma_f32_16x16x32_bf16 v[102:105], v[178:181], v[198:201], v[102:105]
	v_mfma_f32_16x16x32_bf16 v[86:89], v[174:177], v[202:205], v[86:89]
	v_mfma_f32_16x16x32_bf16 v[86:89], v[178:181], v[206:209], v[86:89]
	v_mfma_f32_16x16x32_bf16 v[70:73], v[174:177], v[210:213], v[70:73]
	v_mfma_f32_16x16x32_bf16 v[70:73], v[178:181], v[214:217], v[70:73]
	s_setprio 0
	s_barrier
	s_add_i32 s46, s46, s19
	v_lshl_add_u64 v[148:149], s[12:13], 0, v[134:135]
	s_mov_b32 m0, s46
	ds_read_b128 v[182:185], v152 offset:16384
	ds_read_b128 v[186:189], v152 offset:17408
	ds_read_b128 v[190:193], v152 offset:18432
	ds_read_b128 v[198:201], v152 offset:19456
	ds_read_b128 v[202:205], v152 offset:20480
	ds_read_b128 v[206:209], v152 offset:21504
	ds_read_b128 v[210:213], v152 offset:22528
	ds_read_b128 v[214:217], v152 offset:23552
	global_load_lds_dwordx4 v[148:149], off
	s_add_i32 m0, s46, 0x2000
	s_add_u32 s46, s12, 0x40000
	v_lshl_add_u64 v[218:219], s[12:13], 0, v[138:139]
	s_addc_u32 s47, s13, 0
	s_add_i32 s48, s48, s19
	global_load_lds_dwordx4 v[218:219], off
	v_lshl_add_u64 v[220:221], s[46:47], 0, v[134:135]
	s_mov_b32 m0, s48
	v_lshl_add_u64 v[222:223], s[14:15], 0, v[136:137]
	global_load_lds_dwordx4 v[220:221], off
	v_lshl_add_u64 v[220:221], s[46:47], 0, v[138:139]
	s_add_i32 m0, s48, 0x2000
	s_nop 0
	global_load_lds_dwordx4 v[220:221], off
	v_lshl_add_u64 v[220:221], s[14:15], 0, v[2:3]
	s_mov_b32 m0, s22
	s_nop 0
	global_load_lds_dwordx4 v[220:221], off
	s_mov_b32 m0, s23
	s_nop 0
	global_load_lds_dwordx4 v[222:223], off
	s_waitcnt vmcnt(8)
	s_waitcnt lgkmcnt(0)
	s_barrier
; #define PG8_STAGE(bufoff, gbase, voff) do { _Pragma("unroll") for (int _i = 0; _i < 2; ++_i) \
;         __builtin_amdgcn_global_load_lds((const unsigned*)((const char*)(gbase) + (voff)[_i]), (PG8_LAS unsigned*)(lds + (bufoff) + ldsw + _i * 8192), 16, 0, 0); } while (0)
; #define PG8_LDA(dst, b, h) do { _Pragma("unroll") for (int m = 0; m < 4; ++m) _Pragma("unroll") for (int k = 0; k < 2; ++k) dst[m][k] = *(const PG8_LAS bf16x8*)(lds + PG8_SA(b, h) + aoff + m * 2048 + k * 1024); } while (0)
; #define PG8_LDB(dst, b, h) do { _Pragma("unroll") for (int n = 0; n < 2; ++n) _Pragma("unroll") for (int k = 0; k < 2; ++k) dst[n][k] = *(const PG8_LAS bf16x8*)(lds + PG8_SB(b, h) + boff + n * 2048 + k * 1024); } while (0)
; #define PG8_MMA(ai, bj, At, Bt) do { __builtin_amdgcn_s_setprio(1); _Pragma("unroll") for (int m = 0; m < 4; ++m) _Pragma("unroll") for (int n = 0; n < 2; ++n) _Pragma("unroll") for (int k = 0; k < 2; ++k) \
;         acc[ai][bj][m][n] = __builtin_amdgcn_mfma_f32_16x16x32_bf16(Bt[n][k], At[m][k], acc[ai][bj][m][n], 0, 0, 0); __builtin_amdgcn_s_setprio(0); } while (0)
; #define PG8_WAIT_V(n) asm volatile("s_waitcnt vmcnt(" #n ")" ::: "memory")
; #define PG8_WAIT_L(n) asm volatile("s_waitcnt lgkmcnt(" #n ")" ::: "memory")
; #define PG8_BAR __builtin_amdgcn_s_barrier()
; #define PG8_SCHED __builtin_amdgcn_sched_barrier(0)
; template <class Epi, class Sched, bool ALIGN_EPI = false, bool SP2 = false>
; __device__ __forceinline__ void gemm_phase(PG8_LAS unsigned char* lds, const Gemm g, const Sched& S, const Epi& E, const int tid_in) {
;     ...
;             PG8_WAIT_V(8); PG8_WAIT_L(0); PG8_BAR; PG8_MMA(1, 0, At, B0); PG8_MMA(1, 1, At, B1); PG8_BAR; PG8_SCHED;
;             PG8_LDB(B0, 1, 0); PG8_LDB(B1, 1, 1); PG8_SCHED; PG8_LDA(At, 1, 0); PG8_STAGE(PG8_SA(0, 1), a2 + hstep, voffA);
;             PG8_WAIT_V(8); PG8_WAIT_L(0); PG8_BAR; PG8_MMA(0, 0, At, B0); PG8_MMA(0, 1, At, B1); PG8_BAR; PG8_SCHED;
	s_setprio 1
	s_waitcnt lgkmcnt(0)
	v_mfma_f32_16x16x32_bf16 v[66:69], v[144:147], v[182:185], v[66:69]
	v_mfma_f32_16x16x32_bf16 v[66:69], v[154:157], v[186:189], v[66:69]
	v_mfma_f32_16x16x32_bf16 v[50:53], v[144:147], v[190:193], v[50:53]
	v_mfma_f32_16x16x32_bf16 v[50:53], v[154:157], v[198:201], v[50:53]
	v_mfma_f32_16x16x32_bf16 v[34:37], v[144:147], v[202:205], v[34:37]
	v_mfma_f32_16x16x32_bf16 v[34:37], v[154:157], v[206:209], v[34:37]
	v_mfma_f32_16x16x32_bf16 v[18:21], v[144:147], v[210:213], v[18:21]
	v_mfma_f32_16x16x32_bf16 v[18:21], v[154:157], v[214:217], v[18:21]
	v_mfma_f32_16x16x32_bf16 v[62:65], v[158:161], v[182:185], v[62:65]
	v_mfma_f32_16x16x32_bf16 v[62:65], v[162:165], v[186:189], v[62:65]
	v_mfma_f32_16x16x32_bf16 v[46:49], v[158:161], v[190:193], v[46:49]
	v_mfma_f32_16x16x32_bf16 v[46:49], v[162:165], v[198:201], v[46:49]
	v_mfma_f32_16x16x32_bf16 v[30:33], v[158:161], v[202:205], v[30:33]
	v_mfma_f32_16x16x32_bf16 v[30:33], v[162:165], v[206:209], v[30:33]
	v_mfma_f32_16x16x32_bf16 v[14:17], v[158:161], v[210:213], v[14:17]
	v_mfma_f32_16x16x32_bf16 v[14:17], v[162:165], v[214:217], v[14:17]
	v_mfma_f32_16x16x32_bf16 v[58:61], v[166:169], v[182:185], v[58:61]
	v_mfma_f32_16x16x32_bf16 v[58:61], v[170:173], v[186:189], v[58:61]
	v_mfma_f32_16x16x32_bf16 v[42:45], v[166:169], v[190:193], v[42:45]
	v_mfma_f32_16x16x32_bf16 v[42:45], v[170:173], v[198:201], v[42:45]
	v_mfma_f32_16x16x32_bf16 v[26:29], v[166:169], v[202:205], v[26:29]
	v_mfma_f32_16x16x32_bf16 v[26:29], v[170:173], v[206:209], v[26:29]
	v_mfma_f32_16x16x32_bf16 v[10:13], v[166:169], v[210:213], v[10:13]
	v_mfma_f32_16x16x32_bf16 v[10:13], v[170:173], v[214:217], v[10:13]
	v_mfma_f32_16x16x32_bf16 v[54:57], v[174:177], v[182:185], v[54:57]
	v_mfma_f32_16x16x32_bf16 v[54:57], v[178:181], v[186:189], v[54:57]
	v_mfma_f32_16x16x32_bf16 v[38:41], v[174:177], v[190:193], v[38:41]
	v_mfma_f32_16x16x32_bf16 v[38:41], v[178:181], v[198:201], v[38:41]
	v_mfma_f32_16x16x32_bf16 v[22:25], v[174:177], v[202:205], v[22:25]
	v_mfma_f32_16x16x32_bf16 v[22:25], v[178:181], v[206:209], v[22:25]
	v_mfma_f32_16x16x32_bf16 v[6:9], v[174:177], v[210:213], v[6:9]
	v_mfma_f32_16x16x32_bf16 v[6:9], v[178:181], v[214:217], v[6:9]
	s_setprio 0
	s_barrier
	s_add_i32 s46, 0, 0x18000
	v_add_u32_e32 v153, s46, v150
	s_add_i32 s47, 0, 0x1c000
	ds_read_b128 v[144:147], v153
	ds_read_b128 v[154:157], v153 offset:1024
	ds_read_b128 v[158:161], v153 offset:2048
	ds_read_b128 v[162:165], v153 offset:3072
	v_add_u32_e32 v153, s47, v150
	ds_read_b128 v[166:169], v153
	ds_read_b128 v[170:173], v153 offset:1024
	ds_read_b128 v[174:177], v153 offset:2048
	ds_read_b128 v[178:181], v153 offset:3072
	s_add_u32 s14, s14, 0x40000
	s_addc_u32 s15, s15, 0
	s_mov_b32 m0, s26
	v_lshl_add_u64 v[224:225], s[14:15], 0, v[2:3]
	ds_read_b128 v[182:185], v152 offset:32768
	ds_read_b128 v[186:189], v152 offset:33792
	ds_read_b128 v[190:193], v152 offset:34816
	ds_read_b128 v[198:201], v152 offset:35840
	ds_read_b128 v[202:205], v152 offset:36864
	ds_read_b128 v[206:209], v152 offset:37888
	ds_read_b128 v[210:213], v152 offset:38912
	ds_read_b128 v[214:217], v152 offset:39936
	global_load_lds_dwordx4 v[224:225], off
	v_lshl_add_u64 v[224:225], s[14:15], 0, v[136:137]
	s_mov_b32 m0, s27
	s_nop 0
	global_load_lds_dwordx4 v[224:225], off
	s_waitcnt vmcnt(8)
	s_waitcnt lgkmcnt(0)
	s_barrier
	s_setprio 1
	s_waitcnt lgkmcnt(0)
	v_mfma_f32_16x16x32_bf16 v[130:133], v[144:147], v[182:185], v[130:133]
	v_mfma_f32_16x16x32_bf16 v[130:133], v[154:157], v[186:189], v[130:133]
	v_mfma_f32_16x16x32_bf16 v[114:117], v[144:147], v[190:193], v[114:117]
	v_mfma_f32_16x16x32_bf16 v[114:117], v[154:157], v[198:201], v[114:117]
	v_mfma_f32_16x16x32_bf16 v[98:101], v[144:147], v[202:205], v[98:101]
	v_mfma_f32_16x16x32_bf16 v[98:101], v[154:157], v[206:209], v[98:101]
	v_mfma_f32_16x16x32_bf16 v[82:85], v[144:147], v[210:213], v[82:85]
	v_mfma_f32_16x16x32_bf16 v[82:85], v[154:157], v[214:217], v[82:85]
	v_mfma_f32_16x16x32_bf16 v[126:129], v[158:161], v[182:185], v[126:129]
	v_mfma_f32_16x16x32_bf16 v[126:129], v[162:165], v[186:189], v[126:129]
	v_mfma_f32_16x16x32_bf16 v[110:113], v[158:161], v[190:193], v[110:113]
	v_mfma_f32_16x16x32_bf16 v[110:113], v[162:165], v[198:201], v[110:113]
	v_mfma_f32_16x16x32_bf16 v[94:97], v[158:161], v[202:205], v[94:97]
	v_mfma_f32_16x16x32_bf16 v[94:97], v[162:165], v[206:209], v[94:97]
	v_mfma_f32_16x16x32_bf16 v[78:81], v[158:161], v[210:213], v[78:81]
	v_mfma_f32_16x16x32_bf16 v[78:81], v[162:165], v[214:217], v[78:81]
	v_mfma_f32_16x16x32_bf16 v[122:125], v[166:169], v[182:185], v[122:125]
	v_mfma_f32_16x16x32_bf16 v[122:125], v[170:173], v[186:189], v[122:125]
	v_mfma_f32_16x16x32_bf16 v[106:109], v[166:169], v[190:193], v[106:109]
	v_mfma_f32_16x16x32_bf16 v[106:109], v[170:173], v[198:201], v[106:109]
	v_mfma_f32_16x16x32_bf16 v[90:93], v[166:169], v[202:205], v[90:93]
	v_mfma_f32_16x16x32_bf16 v[90:93], v[170:173], v[206:209], v[90:93]
	v_mfma_f32_16x16x32_bf16 v[74:77], v[166:169], v[210:213], v[74:77]
	v_mfma_f32_16x16x32_bf16 v[74:77], v[170:173], v[214:217], v[74:77]
	v_mfma_f32_16x16x32_bf16 v[118:121], v[174:177], v[182:185], v[118:121]
	v_mfma_f32_16x16x32_bf16 v[118:121], v[178:181], v[186:189], v[118:121]
	v_mfma_f32_16x16x32_bf16 v[102:105], v[174:177], v[190:193], v[102:105]
	v_mfma_f32_16x16x32_bf16 v[102:105], v[178:181], v[198:201], v[102:105]
	v_mfma_f32_16x16x32_bf16 v[86:89], v[174:177], v[202:205], v[86:89]
	v_mfma_f32_16x16x32_bf16 v[86:89], v[178:181], v[206:209], v[86:89]
	v_mfma_f32_16x16x32_bf16 v[70:73], v[174:177], v[210:213], v[70:73]
	v_mfma_f32_16x16x32_bf16 v[70:73], v[178:181], v[214:217], v[70:73]
	s_setprio 0
	s_barrier
; #define PG8_STAGE(bufoff, gbase, voff) do { _Pragma("unroll") for (int _i = 0; _i < 2; ++_i) \
;         __builtin_amdgcn_global_load_lds((const unsigned*)((const char*)(gbase) + (voff)[_i]), (PG8_LAS unsigned*)(lds + (bufoff) + ldsw + _i * 8192), 16, 0, 0); } while (0)
; #define PG8_LDA(dst, b, h) do { _Pragma("unroll") for (int m = 0; m < 4; ++m) _Pragma("unroll") for (int k = 0; k < 2; ++k) dst[m][k] = *(const PG8_LAS bf16x8*)(lds + PG8_SA(b, h) + aoff + m * 2048 + k * 1024); } while (0)
; #define PG8_MMA(ai, bj, At, Bt) do { __builtin_amdgcn_s_setprio(1); _Pragma("unroll") for (int m = 0; m < 4; ++m) _Pragma("unroll") for (int n = 0; n < 2; ++n) _Pragma("unroll") for (int k = 0; k < 2; ++k) \
;         acc[ai][bj][m][n] = __builtin_amdgcn_mfma_f32_16x16x32_bf16(Bt[n][k], At[m][k], acc[ai][bj][m][n], 0, 0, 0); __builtin_amdgcn_s_setprio(0); } while (0)
; #define PG8_WAIT_V(n) asm volatile("s_waitcnt vmcnt(" #n ")" ::: "memory")
; #define PG8_WAIT_L(n) asm volatile("s_waitcnt lgkmcnt(" #n ")" ::: "memory")
; #define PG8_BAR __builtin_amdgcn_s_barrier()
; #define PG8_SCHED __builtin_amdgcn_sched_barrier(0)
; template <class Epi, class Sched, bool ALIGN_EPI = false, bool SP2 = false>
; __device__ __forceinline__ void gemm_phase(PG8_LAS unsigned char* lds, const Gemm g, const Sched& S, const Epi& E, const int tid_in) {
;     ...
;             PG8_LDA(At, 1, 1); PG8_STAGE(PG8_SB(1, 0), b3, voffB); PG8_STAGE(PG8_SB(1, 1), b3 + hstep, voffB); PG8_STAGE(PG8_SA(1, 0), a3, voffA);
;             PG8_WAIT_V(8); PG8_WAIT_L(0); PG8_BAR; PG8_MMA(1, 0, At, B0); PG8_MMA(1, 1, At, B1); PG8_BAR; PG8_SCHED;
;     __device__ __forceinline__ void operator()(const f32x4 (&acc)[2][2][4][2], const Unit& u, int wr, int wc, int fr, int fq) const {
;     ...
;         float rs[2][4];
; #pragma unroll
;         for (int ai = 0; ai < 2; ++ai)
; #pragma unroll
;             for (int m = 0; m < 4; ++m) rs[ai][m] = rowss[row0 + ai * HALF + m * 16];
	s_add_i32 s14, s46, s19
	v_lshl_add_u64 v[148:149], v[148:149], 0, s[28:29]
	s_mov_b32 m0, s14
	ds_read_b128 v[182:185], v152 offset:49152
	ds_read_b128 v[186:189], v152 offset:50176
	ds_read_b128 v[190:193], v152 offset:51200
	ds_read_b128 v[198:201], v152 offset:52224
	ds_read_b128 v[202:205], v152 offset:53248
	ds_read_b128 v[206:209], v152 offset:54272
	ds_read_b128 v[210:213], v152 offset:55296
	ds_read_b128 v[214:217], v152 offset:56320
	global_load_lds_dwordx4 v[148:149], off
	s_add_i32 m0, s14, 0x2000
	s_add_u32 s12, s12, 0x40080
	v_lshl_add_u64 v[148:149], v[218:219], 0, s[28:29]
	s_addc_u32 s13, s13, 0
	s_add_i32 s14, s47, s19
	global_load_lds_dwordx4 v[148:149], off
	v_lshl_add_u64 v[148:149], s[12:13], 0, v[134:135]
	s_mov_b32 m0, s14
	s_nop 0
	global_load_lds_dwordx4 v[148:149], off
	v_lshl_add_u64 v[148:149], s[12:13], 0, v[138:139]
	s_add_i32 m0, s14, 0x2000
	s_nop 0
	global_load_lds_dwordx4 v[148:149], off
	v_lshl_add_u64 v[148:149], v[220:221], 0, s[28:29]
	s_mov_b32 m0, s30
	s_nop 0
	global_load_lds_dwordx4 v[148:149], off
	v_lshl_add_u64 v[148:149], v[222:223], 0, s[28:29]
	s_mov_b32 m0, s31
	s_nop 0
	global_load_lds_dwordx4 v[148:149], off
	s_waitcnt vmcnt(8)
	s_waitcnt lgkmcnt(0)
	s_cmp_lg_u32 s45, 12
	s_cbranch_scc1 .Lrs_in_skip
	v_lshl_add_u32 v148, s38, 8, v5
	v_ashrrev_i32_e32 v149, 31, v148
	v_lshl_add_u64 v[148:149], v[148:149], 2, s[6:7]
	global_load_dword v226, v[148:149], off
	global_load_dword v227, v[148:149], off offset:64
	global_load_dword v228, v[148:149], off offset:128
	global_load_dword v229, v[148:149], off offset:192
	global_load_dword v238, v[148:149], off offset:512
	global_load_dword v239, v[148:149], off offset:576
	global_load_dword v240, v[148:149], off offset:640
	global_load_dword v241, v[148:149], off offset:704
.Lrs_in_skip:
	s_barrier
	s_setprio 1
	s_waitcnt lgkmcnt(0)
	v_mfma_f32_16x16x32_bf16 v[66:69], v[144:147], v[182:185], v[66:69]
	v_mfma_f32_16x16x32_bf16 v[66:69], v[154:157], v[186:189], v[66:69]
	v_mfma_f32_16x16x32_bf16 v[50:53], v[144:147], v[190:193], v[50:53]
	v_mfma_f32_16x16x32_bf16 v[50:53], v[154:157], v[198:201], v[50:53]
	v_mfma_f32_16x16x32_bf16 v[34:37], v[144:147], v[202:205], v[34:37]
	v_mfma_f32_16x16x32_bf16 v[34:37], v[154:157], v[206:209], v[34:37]
	v_mfma_f32_16x16x32_bf16 v[18:21], v[144:147], v[210:213], v[18:21]
	v_mfma_f32_16x16x32_bf16 v[18:21], v[154:157], v[214:217], v[18:21]
	v_mfma_f32_16x16x32_bf16 v[62:65], v[158:161], v[182:185], v[62:65]
	v_mfma_f32_16x16x32_bf16 v[62:65], v[162:165], v[186:189], v[62:65]
	v_mfma_f32_16x16x32_bf16 v[46:49], v[158:161], v[190:193], v[46:49]
	v_mfma_f32_16x16x32_bf16 v[46:49], v[162:165], v[198:201], v[46:49]
	v_mfma_f32_16x16x32_bf16 v[30:33], v[158:161], v[202:205], v[30:33]
	v_mfma_f32_16x16x32_bf16 v[30:33], v[162:165], v[206:209], v[30:33]
	v_mfma_f32_16x16x32_bf16 v[14:17], v[158:161], v[210:213], v[14:17]
	v_mfma_f32_16x16x32_bf16 v[14:17], v[162:165], v[214:217], v[14:17]
	v_mfma_f32_16x16x32_bf16 v[58:61], v[166:169], v[182:185], v[58:61]
	v_mfma_f32_16x16x32_bf16 v[58:61], v[170:173], v[186:189], v[58:61]
	v_mfma_f32_16x16x32_bf16 v[42:45], v[166:169], v[190:193], v[42:45]
	v_mfma_f32_16x16x32_bf16 v[42:45], v[170:173], v[198:201], v[42:45]
	v_mfma_f32_16x16x32_bf16 v[26:29], v[166:169], v[202:205], v[26:29]
	v_mfma_f32_16x16x32_bf16 v[26:29], v[170:173], v[206:209], v[26:29]
	v_mfma_f32_16x16x32_bf16 v[10:13], v[166:169], v[210:213], v[10:13]
	v_mfma_f32_16x16x32_bf16 v[10:13], v[170:173], v[214:217], v[10:13]
	v_mfma_f32_16x16x32_bf16 v[54:57], v[174:177], v[182:185], v[54:57]
	v_mfma_f32_16x16x32_bf16 v[54:57], v[178:181], v[186:189], v[54:57]
	v_mfma_f32_16x16x32_bf16 v[38:41], v[174:177], v[190:193], v[38:41]
	v_mfma_f32_16x16x32_bf16 v[38:41], v[178:181], v[198:201], v[38:41]
	v_mfma_f32_16x16x32_bf16 v[22:25], v[174:177], v[202:205], v[22:25]
	v_mfma_f32_16x16x32_bf16 v[22:25], v[178:181], v[206:209], v[22:25]
	v_mfma_f32_16x16x32_bf16 v[6:9], v[174:177], v[210:213], v[6:9]
	v_mfma_f32_16x16x32_bf16 v[6:9], v[178:181], v[214:217], v[6:9]
	s_setprio 0
	s_barrier
	s_add_i32 s45, s45, 2
	s_add_u32 s42, s42, 0x100
	s_addc_u32 s43, s43, 0
	s_add_u32 s25, s25, 0x100
	s_addc_u32 s39, s39, 0
	s_cmp_gt_u32 s45, 13
	s_cbranch_scc0 .LBB0_93
	s_and_b64 vcc, exec, s[8:9]
	s_cbranch_vccz .LBB0_96
	s_barrier

; #define PG8_STAGE(bufoff, gbase, voff) do { _Pragma("unroll") for (int _i = 0; _i < 2; ++_i) \
;         __builtin_amdgcn_global_load_lds((const unsigned*)((const char*)(gbase) + (voff)[_i]), (PG8_LAS unsigned*)(lds + (bufoff) + ldsw + _i * 8192), 16, 0, 0); } while (0)
; #define PG8_LDA(dst, b, h) do { _Pragma("unroll") for (int m = 0; m < 4; ++m) _Pragma("unroll") for (int k = 0; k < 2; ++k) dst[m][k] = *(const PG8_LAS bf16x8*)(lds + PG8_SA(b, h) + aoff + m * 2048 + k * 1024); } while (0)
; #define PG8_LDB(dst, b, h) do { _Pragma("unroll") for (int n = 0; n < 2; ++n) _Pragma("unroll") for (int k = 0; k < 2; ++k) dst[n][k] = *(const PG8_LAS bf16x8*)(lds + PG8_SB(b, h) + boff + n * 2048 + k * 1024); } while (0)
; #define PG8_MMA(ai, bj, At, Bt) do { __builtin_amdgcn_s_setprio(1); _Pragma("unroll") for (int m = 0; m < 4; ++m) _Pragma("unroll") for (int n = 0; n < 2; ++n) _Pragma("unroll") for (int k = 0; k < 2; ++k) \
;         acc[ai][bj][m][n] = __builtin_amdgcn_mfma_f32_16x16x32_bf16(Bt[n][k], At[m][k], acc[ai][bj][m][n], 0, 0, 0); __builtin_amdgcn_s_setprio(0); } while (0)
; #define PG8_WAIT_V(n) asm volatile("s_waitcnt vmcnt(" #n ")" ::: "memory")
; #define PG8_WAIT_L(n) asm volatile("s_waitcnt lgkmcnt(" #n ")" ::: "memory")
; template <class Epi, class Sched, bool ALIGN_EPI = false, bool SP2 = false>
; __device__ __forceinline__ void gemm_phase(PG8_LAS unsigned char* lds, const Gemm g, const Sched& S, const Epi& E, const int tid_in) {
;     ...
;             const bool last = (t == nt - 2);
;             const char* a1 = cA + (size_t)(t + 1) * kstep;
;             const char* a2 = last ? nA : cA + (size_t)(t + 2) * kstep; const char* b2 = last ? nB : cB + (size_t)(t + 2) * kstep;
;             const char* a3 = a2 + kstep; const char* b3 = b2 + kstep;
;             if (last && has_next) S.a_ready(nxt);
;             if constexpr (SP2) {
;             PG8_LDB(B0, 0, 0); PG8_LDB(B1, 0, 1); PG8_SCHED; PG8_LDA(At, 0, 0); PG8_STAGE(PG8_SA(1, 1), a1 + hstep, voffA);
;             PG8_WAIT_V(8); PG8_WAIT_L(0); PG8_BAR; PG8_MMA(0, 0, At, B0); PG8_MMA(0, 1, At, B1); PG8_BAR; PG8_SCHED;
;             PG8_LDA(At, 0, 1); PG8_STAGE(PG8_SB(0, 0), b2, voffB); PG8_STAGE(PG8_SB(0, 1), b2 + hstep, voffB); PG8_STAGE(PG8_SA(0, 0), a2, voffA);
;             PG8_WAIT_V(8); PG8_WAIT_L(0); PG8_BAR; PG8_MMA(1, 0, At, B0); PG8_MMA(1, 1, At, B1); PG8_BAR; PG8_SCHED;
.LBB0_154:
	s_add_u32 s12, s10, 0xfffc0080
	s_addc_u32 s13, s11, -1
	s_add_i32 s46, 0, 0x10000
	s_cmp_eq_u32 s45, 12
	s_cselect_b32 s15, s25, s13
	s_cselect_b32 s14, s41, s12
	v_add_u32_e32 v144, s46, v146
	s_cselect_b32 s13, s21, s44
	s_cselect_b32 s12, s42, s43
	s_add_i32 s48, 0, 0x14000
	ds_read_b128 v[150:153], v144
	ds_read_b128 v[154:157], v144 offset:1024
	ds_read_b128 v[158:161], v144 offset:2048
	ds_read_b128 v[162:165], v144 offset:3072
	v_add_u32_e32 v144, s48, v146
	ds_read_b128 v[166:169], v144
	ds_read_b128 v[170:173], v144 offset:1024
	ds_read_b128 v[174:177], v144 offset:2048
	ds_read_b128 v[178:181], v144 offset:3072
	v_lshl_add_u64 v[144:145], s[10:11], 0, v[140:141]
	s_add_i32 m0, s18, 0xc000
	ds_read_b128 v[182:185], v148
	ds_read_b128 v[186:189], v148 offset:1024
	ds_read_b128 v[190:193], v148 offset:2048
	ds_read_b128 v[198:201], v148 offset:3072
	ds_read_b128 v[202:205], v148 offset:4096
	ds_read_b128 v[206:209], v148 offset:5120
	ds_read_b128 v[210:213], v148 offset:6144
	ds_read_b128 v[214:217], v148 offset:7168
	global_load_lds_dwordx4 v[144:145], off
	v_lshl_add_u64 v[144:145], s[10:11], 0, v[142:143]
	s_add_i32 m0, s18, 0xe000
	s_nop 0
	global_load_lds_dwordx4 v[144:145], off
	s_waitcnt vmcnt(8)
	s_waitcnt lgkmcnt(0)
	s_barrier
	s_setprio 1
	s_waitcnt lgkmcnt(0)
	v_mfma_f32_16x16x32_bf16 v[130:133], v[150:153], v[182:185], v[130:133]
	v_mfma_f32_16x16x32_bf16 v[130:133], v[154:157], v[186:189], v[130:133]
	v_mfma_f32_16x16x32_bf16 v[114:117], v[150:153], v[190:193], v[114:117]
	v_mfma_f32_16x16x32_bf16 v[114:117], v[154:157], v[198:201], v[114:117]
	v_mfma_f32_16x16x32_bf16 v[98:101], v[150:153], v[202:205], v[98:101]
	v_mfma_f32_16x16x32_bf16 v[98:101], v[154:157], v[206:209], v[98:101]
	v_mfma_f32_16x16x32_bf16 v[82:85], v[150:153], v[210:213], v[82:85]
	v_mfma_f32_16x16x32_bf16 v[82:85], v[154:157], v[214:217], v[82:85]
	v_mfma_f32_16x16x32_bf16 v[126:129], v[158:161], v[182:185], v[126:129]
	v_mfma_f32_16x16x32_bf16 v[126:129], v[162:165], v[186:189], v[126:129]
	v_mfma_f32_16x16x32_bf16 v[106:109], v[158:161], v[190:193], v[106:109]
	v_mfma_f32_16x16x32_bf16 v[106:109], v[162:165], v[198:201], v[106:109]
	v_mfma_f32_16x16x32_bf16 v[94:97], v[158:161], v[202:205], v[94:97]
	v_mfma_f32_16x16x32_bf16 v[94:97], v[162:165], v[206:209], v[94:97]
	v_mfma_f32_16x16x32_bf16 v[78:81], v[158:161], v[210:213], v[78:81]
	v_mfma_f32_16x16x32_bf16 v[78:81], v[162:165], v[214:217], v[78:81]
	v_mfma_f32_16x16x32_bf16 v[122:125], v[166:169], v[182:185], v[122:125]
	v_mfma_f32_16x16x32_bf16 v[122:125], v[170:173], v[186:189], v[122:125]
	v_mfma_f32_16x16x32_bf16 v[110:113], v[166:169], v[190:193], v[110:113]
	v_mfma_f32_16x16x32_bf16 v[110:113], v[170:173], v[198:201], v[110:113]
	v_mfma_f32_16x16x32_bf16 v[90:93], v[166:169], v[202:205], v[90:93]
	v_mfma_f32_16x16x32_bf16 v[90:93], v[170:173], v[206:209], v[90:93]
	v_mfma_f32_16x16x32_bf16 v[74:77], v[166:169], v[210:213], v[74:77]
	v_mfma_f32_16x16x32_bf16 v[74:77], v[170:173], v[214:217], v[74:77]
	v_mfma_f32_16x16x32_bf16 v[118:121], v[174:177], v[182:185], v[118:121]
	v_mfma_f32_16x16x32_bf16 v[118:121], v[178:181], v[186:189], v[118:121]
	v_mfma_f32_16x16x32_bf16 v[102:105], v[174:177], v[190:193], v[102:105]
	v_mfma_f32_16x16x32_bf16 v[102:105], v[178:181], v[198:201], v[102:105]
	v_mfma_f32_16x16x32_bf16 v[86:89], v[174:177], v[202:205], v[86:89]
	v_mfma_f32_16x16x32_bf16 v[86:89], v[178:181], v[206:209], v[86:89]
	v_mfma_f32_16x16x32_bf16 v[70:73], v[174:177], v[210:213], v[70:73]
	v_mfma_f32_16x16x32_bf16 v[70:73], v[178:181], v[214:217], v[70:73]
	s_setprio 0
	s_barrier
	s_add_i32 s46, s46, s17
	v_lshl_add_u64 v[144:145], s[12:13], 0, v[136:137]
	s_mov_b32 m0, s46
	ds_read_b128 v[182:185], v148 offset:16384
	ds_read_b128 v[186:189], v148 offset:17408
	ds_read_b128 v[190:193], v148 offset:18432
	ds_read_b128 v[198:201], v148 offset:19456
	ds_read_b128 v[202:205], v148 offset:20480
	ds_read_b128 v[206:209], v148 offset:21504
	ds_read_b128 v[210:213], v148 offset:22528
	ds_read_b128 v[214:217], v148 offset:23552
	global_load_lds_dwordx4 v[144:145], off
	s_add_i32 m0, s46, 0x2000
	s_add_u32 s46, s12, 0x40000
	v_lshl_add_u64 v[218:219], s[12:13], 0, v[2:3]
	s_addc_u32 s47, s13, 0
	s_add_i32 s48, s48, s17
	global_load_lds_dwordx4 v[218:219], off
	v_lshl_add_u64 v[220:221], s[46:47], 0, v[136:137]
	s_mov_b32 m0, s48
	v_lshl_add_u64 v[222:223], s[14:15], 0, v[134:135]
	global_load_lds_dwordx4 v[220:221], off
	v_lshl_add_u64 v[220:221], s[46:47], 0, v[2:3]
	s_add_i32 m0, s48, 0x2000
	s_nop 0
	global_load_lds_dwordx4 v[220:221], off
	v_lshl_add_u64 v[220:221], s[14:15], 0, v[138:139]
	s_mov_b32 m0, s18
	s_nop 0
	global_load_lds_dwordx4 v[220:221], off
	s_mov_b32 m0, s19
	s_nop 0
	global_load_lds_dwordx4 v[222:223], off
	s_waitcnt vmcnt(8)
	s_waitcnt lgkmcnt(0)
	s_barrier
; #define PG8_STAGE(bufoff, gbase, voff) do { _Pragma("unroll") for (int _i = 0; _i < 2; ++_i) \
;         __builtin_amdgcn_global_load_lds((const unsigned*)((const char*)(gbase) + (voff)[_i]), (PG8_LAS unsigned*)(lds + (bufoff) + ldsw + _i * 8192), 16, 0, 0); } while (0)
; #define PG8_LDA(dst, b, h) do { _Pragma("unroll") for (int m = 0; m < 4; ++m) _Pragma("unroll") for (int k = 0; k < 2; ++k) dst[m][k] = *(const PG8_LAS bf16x8*)(lds + PG8_SA(b, h) + aoff + m * 2048 + k * 1024); } while (0)
; #define PG8_LDB(dst, b, h) do { _Pragma("unroll") for (int n = 0; n < 2; ++n) _Pragma("unroll") for (int k = 0; k < 2; ++k) dst[n][k] = *(const PG8_LAS bf16x8*)(lds + PG8_SB(b, h) + boff + n * 2048 + k * 1024); } while (0)
; #define PG8_MMA(ai, bj, At, Bt) do { __builtin_amdgcn_s_setprio(1); _Pragma("unroll") for (int m = 0; m < 4; ++m) _Pragma("unroll") for (int n = 0; n < 2; ++n) _Pragma("unroll") for (int k = 0; k < 2; ++k) \
;         acc[ai][bj][m][n] = __builtin_amdgcn_mfma_f32_16x16x32_bf16(Bt[n][k], At[m][k], acc[ai][bj][m][n], 0, 0, 0); __builtin_amdgcn_s_setprio(0); } while (0)
; #define PG8_WAIT_V(n) asm volatile("s_waitcnt vmcnt(" #n ")" ::: "memory")
; #define PG8_WAIT_L(n) asm volatile("s_waitcnt lgkmcnt(" #n ")" ::: "memory")
; #define PG8_BAR __builtin_amdgcn_s_barrier()
; #define PG8_SCHED __builtin_amdgcn_sched_barrier(0)
; template <class Epi, class Sched, bool ALIGN_EPI = false, bool SP2 = false>
; __device__ __forceinline__ void gemm_phase(PG8_LAS unsigned char* lds, const Gemm g, const Sched& S, const Epi& E, const int tid_in) {
;     ...
;             PG8_WAIT_V(8); PG8_WAIT_L(0); PG8_BAR; PG8_MMA(1, 0, At, B0); PG8_MMA(1, 1, At, B1); PG8_BAR; PG8_SCHED;
;             PG8_LDB(B0, 1, 0); PG8_LDB(B1, 1, 1); PG8_SCHED; PG8_LDA(At, 1, 0); PG8_STAGE(PG8_SA(0, 1), a2 + hstep, voffA);
;             PG8_WAIT_V(8); PG8_WAIT_L(0); PG8_BAR; PG8_MMA(0, 0, At, B0); PG8_MMA(0, 1, At, B1); PG8_BAR; PG8_SCHED;
	s_setprio 1
	s_waitcnt lgkmcnt(0)
	v_mfma_f32_16x16x32_bf16 v[66:69], v[150:153], v[182:185], v[66:69]
	v_mfma_f32_16x16x32_bf16 v[66:69], v[154:157], v[186:189], v[66:69]
	v_mfma_f32_16x16x32_bf16 v[50:53], v[150:153], v[190:193], v[50:53]
	v_mfma_f32_16x16x32_bf16 v[50:53], v[154:157], v[198:201], v[50:53]
	v_mfma_f32_16x16x32_bf16 v[34:37], v[150:153], v[202:205], v[34:37]
	v_mfma_f32_16x16x32_bf16 v[34:37], v[154:157], v[206:209], v[34:37]
	v_mfma_f32_16x16x32_bf16 v[18:21], v[150:153], v[210:213], v[18:21]
	v_mfma_f32_16x16x32_bf16 v[18:21], v[154:157], v[214:217], v[18:21]
	v_mfma_f32_16x16x32_bf16 v[62:65], v[158:161], v[182:185], v[62:65]
	v_mfma_f32_16x16x32_bf16 v[62:65], v[162:165], v[186:189], v[62:65]
	v_mfma_f32_16x16x32_bf16 v[46:49], v[158:161], v[190:193], v[46:49]
	v_mfma_f32_16x16x32_bf16 v[46:49], v[162:165], v[198:201], v[46:49]
	v_mfma_f32_16x16x32_bf16 v[30:33], v[158:161], v[202:205], v[30:33]
	v_mfma_f32_16x16x32_bf16 v[30:33], v[162:165], v[206:209], v[30:33]
	v_mfma_f32_16x16x32_bf16 v[14:17], v[158:161], v[210:213], v[14:17]
	v_mfma_f32_16x16x32_bf16 v[14:17], v[162:165], v[214:217], v[14:17]
	v_mfma_f32_16x16x32_bf16 v[58:61], v[166:169], v[182:185], v[58:61]
	v_mfma_f32_16x16x32_bf16 v[58:61], v[170:173], v[186:189], v[58:61]
	v_mfma_f32_16x16x32_bf16 v[42:45], v[166:169], v[190:193], v[42:45]
	v_mfma_f32_16x16x32_bf16 v[42:45], v[170:173], v[198:201], v[42:45]
	v_mfma_f32_16x16x32_bf16 v[26:29], v[166:169], v[202:205], v[26:29]
	v_mfma_f32_16x16x32_bf16 v[26:29], v[170:173], v[206:209], v[26:29]
	v_mfma_f32_16x16x32_bf16 v[10:13], v[166:169], v[210:213], v[10:13]
	v_mfma_f32_16x16x32_bf16 v[10:13], v[170:173], v[214:217], v[10:13]
	v_mfma_f32_16x16x32_bf16 v[54:57], v[174:177], v[182:185], v[54:57]
	v_mfma_f32_16x16x32_bf16 v[54:57], v[178:181], v[186:189], v[54:57]
	v_mfma_f32_16x16x32_bf16 v[38:41], v[174:177], v[190:193], v[38:41]
	v_mfma_f32_16x16x32_bf16 v[38:41], v[178:181], v[198:201], v[38:41]
	v_mfma_f32_16x16x32_bf16 v[22:25], v[174:177], v[202:205], v[22:25]
	v_mfma_f32_16x16x32_bf16 v[22:25], v[178:181], v[206:209], v[22:25]
	v_mfma_f32_16x16x32_bf16 v[6:9], v[174:177], v[210:213], v[6:9]
	v_mfma_f32_16x16x32_bf16 v[6:9], v[178:181], v[214:217], v[6:9]
	s_setprio 0
	s_barrier
	s_add_i32 s46, 0, 0x18000
	v_add_u32_e32 v149, s46, v146
	s_add_i32 s47, 0, 0x1c000
	ds_read_b128 v[150:153], v149
	ds_read_b128 v[154:157], v149 offset:1024
	ds_read_b128 v[158:161], v149 offset:2048
	ds_read_b128 v[162:165], v149 offset:3072
	v_add_u32_e32 v149, s47, v146
	ds_read_b128 v[166:169], v149
	ds_read_b128 v[170:173], v149 offset:1024
	ds_read_b128 v[174:177], v149 offset:2048
	ds_read_b128 v[178:181], v149 offset:3072
	s_add_u32 s14, s14, 0x40000
	s_addc_u32 s15, s15, 0
	s_mov_b32 m0, s22
	v_lshl_add_u64 v[224:225], s[14:15], 0, v[138:139]
	ds_read_b128 v[182:185], v148 offset:32768
	ds_read_b128 v[186:189], v148 offset:33792
	ds_read_b128 v[190:193], v148 offset:34816
	ds_read_b128 v[198:201], v148 offset:35840
	ds_read_b128 v[202:205], v148 offset:36864
	ds_read_b128 v[206:209], v148 offset:37888
	ds_read_b128 v[210:213], v148 offset:38912
	ds_read_b128 v[214:217], v148 offset:39936
	global_load_lds_dwordx4 v[224:225], off
	v_lshl_add_u64 v[224:225], s[14:15], 0, v[134:135]
	s_mov_b32 m0, s23
	s_nop 0
	global_load_lds_dwordx4 v[224:225], off
	s_waitcnt vmcnt(8)
	s_waitcnt lgkmcnt(0)
	s_barrier
	s_setprio 1
	s_waitcnt lgkmcnt(0)
	v_mfma_f32_16x16x32_bf16 v[130:133], v[150:153], v[182:185], v[130:133]
	v_mfma_f32_16x16x32_bf16 v[130:133], v[154:157], v[186:189], v[130:133]
	v_mfma_f32_16x16x32_bf16 v[114:117], v[150:153], v[190:193], v[114:117]
	v_mfma_f32_16x16x32_bf16 v[114:117], v[154:157], v[198:201], v[114:117]
	v_mfma_f32_16x16x32_bf16 v[98:101], v[150:153], v[202:205], v[98:101]
	v_mfma_f32_16x16x32_bf16 v[98:101], v[154:157], v[206:209], v[98:101]
	v_mfma_f32_16x16x32_bf16 v[82:85], v[150:153], v[210:213], v[82:85]
	v_mfma_f32_16x16x32_bf16 v[82:85], v[154:157], v[214:217], v[82:85]
	v_mfma_f32_16x16x32_bf16 v[126:129], v[158:161], v[182:185], v[126:129]
	v_mfma_f32_16x16x32_bf16 v[126:129], v[162:165], v[186:189], v[126:129]
	v_mfma_f32_16x16x32_bf16 v[106:109], v[158:161], v[190:193], v[106:109]
	v_mfma_f32_16x16x32_bf16 v[106:109], v[162:165], v[198:201], v[106:109]
	v_mfma_f32_16x16x32_bf16 v[94:97], v[158:161], v[202:205], v[94:97]
	v_mfma_f32_16x16x32_bf16 v[94:97], v[162:165], v[206:209], v[94:97]
	v_mfma_f32_16x16x32_bf16 v[78:81], v[158:161], v[210:213], v[78:81]
	v_mfma_f32_16x16x32_bf16 v[78:81], v[162:165], v[214:217], v[78:81]
	v_mfma_f32_16x16x32_bf16 v[122:125], v[166:169], v[182:185], v[122:125]
	v_mfma_f32_16x16x32_bf16 v[122:125], v[170:173], v[186:189], v[122:125]
	v_mfma_f32_16x16x32_bf16 v[110:113], v[166:169], v[190:193], v[110:113]
	v_mfma_f32_16x16x32_bf16 v[110:113], v[170:173], v[198:201], v[110:113]
	v_mfma_f32_16x16x32_bf16 v[90:93], v[166:169], v[202:205], v[90:93]
	v_mfma_f32_16x16x32_bf16 v[90:93], v[170:173], v[206:209], v[90:93]
	v_mfma_f32_16x16x32_bf16 v[74:77], v[166:169], v[210:213], v[74:77]
	v_mfma_f32_16x16x32_bf16 v[74:77], v[170:173], v[214:217], v[74:77]
	v_mfma_f32_16x16x32_bf16 v[118:121], v[174:177], v[182:185], v[118:121]
	v_mfma_f32_16x16x32_bf16 v[118:121], v[178:181], v[186:189], v[118:121]
	v_mfma_f32_16x16x32_bf16 v[102:105], v[174:177], v[190:193], v[102:105]
	v_mfma_f32_16x16x32_bf16 v[102:105], v[178:181], v[198:201], v[102:105]
	v_mfma_f32_16x16x32_bf16 v[86:89], v[174:177], v[202:205], v[86:89]
	v_mfma_f32_16x16x32_bf16 v[86:89], v[178:181], v[206:209], v[86:89]
	v_mfma_f32_16x16x32_bf16 v[70:73], v[174:177], v[210:213], v[70:73]
	v_mfma_f32_16x16x32_bf16 v[70:73], v[178:181], v[214:217], v[70:73]
	s_setprio 0
	s_barrier
; #define PG8_STAGE(bufoff, gbase, voff) do { _Pragma("unroll") for (int _i = 0; _i < 2; ++_i) \
;         __builtin_amdgcn_global_load_lds((const unsigned*)((const char*)(gbase) + (voff)[_i]), (PG8_LAS unsigned*)(lds + (bufoff) + ldsw + _i * 8192), 16, 0, 0); } while (0)
; #define PG8_LDA(dst, b, h) do { _Pragma("unroll") for (int m = 0; m < 4; ++m) _Pragma("unroll") for (int k = 0; k < 2; ++k) dst[m][k] = *(const PG8_LAS bf16x8*)(lds + PG8_SA(b, h) + aoff + m * 2048 + k * 1024); } while (0)
; #define PG8_MMA(ai, bj, At, Bt) do { __builtin_amdgcn_s_setprio(1); _Pragma("unroll") for (int m = 0; m < 4; ++m) _Pragma("unroll") for (int n = 0; n < 2; ++n) _Pragma("unroll") for (int k = 0; k < 2; ++k) \
;         acc[ai][bj][m][n] = __builtin_amdgcn_mfma_f32_16x16x32_bf16(Bt[n][k], At[m][k], acc[ai][bj][m][n], 0, 0, 0); __builtin_amdgcn_s_setprio(0); } while (0)
; #define PG8_WAIT_V(n) asm volatile("s_waitcnt vmcnt(" #n ")" ::: "memory")
; #define PG8_WAIT_L(n) asm volatile("s_waitcnt lgkmcnt(" #n ")" ::: "memory")
; #define PG8_BAR __builtin_amdgcn_s_barrier()
; #define PG8_SCHED __builtin_amdgcn_sched_barrier(0)
; template <class Epi, class Sched, bool ALIGN_EPI = false, bool SP2 = false>
; __device__ __forceinline__ void gemm_phase(PG8_LAS unsigned char* lds, const Gemm g, const Sched& S, const Epi& E, const int tid_in) {
;     ...
;             PG8_LDA(At, 1, 1); PG8_STAGE(PG8_SB(1, 0), b3, voffB); PG8_STAGE(PG8_SB(1, 1), b3 + hstep, voffB); PG8_STAGE(PG8_SA(1, 0), a3, voffA);
;             PG8_WAIT_V(8); PG8_WAIT_L(0); PG8_BAR; PG8_MMA(1, 0, At, B0); PG8_MMA(1, 1, At, B1); PG8_BAR; PG8_SCHED;
;     __device__ __forceinline__ void operator()(const f32x4 (&acc)[2][2][4][2], const Unit& u, int wr, int wc, int fr, int fq) const {
;     ...
;         float rs[2][4];
; #pragma unroll
;         for (int ai = 0; ai < 2; ++ai)
; #pragma unroll
;             for (int m = 0; m < 4; ++m) rs[ai][m] = rowss[row0 + ai * HALF + m * 16];
	s_add_i32 s14, s46, s17
	v_lshl_add_u64 v[144:145], v[144:145], 0, s[28:29]
	s_mov_b32 m0, s14
	ds_read_b128 v[182:185], v148 offset:49152
	ds_read_b128 v[186:189], v148 offset:50176
	ds_read_b128 v[190:193], v148 offset:51200
	ds_read_b128 v[198:201], v148 offset:52224
	ds_read_b128 v[202:205], v148 offset:53248
	ds_read_b128 v[206:209], v148 offset:54272
	ds_read_b128 v[210:213], v148 offset:55296
	ds_read_b128 v[214:217], v148 offset:56320
	global_load_lds_dwordx4 v[144:145], off
	s_add_i32 m0, s14, 0x2000
	s_add_u32 s12, s12, 0x40080
	v_lshl_add_u64 v[144:145], v[218:219], 0, s[28:29]
	s_addc_u32 s13, s13, 0
	s_add_i32 s14, s47, s17
	global_load_lds_dwordx4 v[144:145], off
	v_lshl_add_u64 v[144:145], s[12:13], 0, v[136:137]
	s_mov_b32 m0, s14
	s_nop 0
	global_load_lds_dwordx4 v[144:145], off
	v_lshl_add_u64 v[144:145], s[12:13], 0, v[2:3]
	s_add_i32 m0, s14, 0x2000
	s_nop 0
	global_load_lds_dwordx4 v[144:145], off
	v_lshl_add_u64 v[144:145], v[220:221], 0, s[28:29]
	s_mov_b32 m0, s26
	s_nop 0
	global_load_lds_dwordx4 v[144:145], off
	v_lshl_add_u64 v[144:145], v[222:223], 0, s[28:29]
	s_mov_b32 m0, s27
	s_nop 0
	global_load_lds_dwordx4 v[144:145], off
	s_waitcnt vmcnt(8)
	s_waitcnt lgkmcnt(0)
	s_cmp_lg_u32 s45, 12
	s_cbranch_scc1 .Lrs_gu_skip
	v_lshl_add_u32 v144, s40, 8, v5
	v_ashrrev_i32_e32 v145, 31, v144
	v_lshl_add_u64 v[144:145], v[144:145], 2, s[6:7]
	global_load_dword v226, v[144:145], off
	global_load_dword v227, v[144:145], off offset:64
	global_load_dword v228, v[144:145], off offset:128
	global_load_dword v229, v[144:145], off offset:192
	global_load_dword v238, v[144:145], off offset:512
	global_load_dword v239, v[144:145], off offset:576
	global_load_dword v240, v[144:145], off offset:640
	global_load_dword v241, v[144:145], off offset:704
.Lrs_gu_skip:
	s_barrier
	s_setprio 1
	s_waitcnt lgkmcnt(0)
	v_mfma_f32_16x16x32_bf16 v[66:69], v[150:153], v[182:185], v[66:69]
	v_mfma_f32_16x16x32_bf16 v[66:69], v[154:157], v[186:189], v[66:69]
	v_mfma_f32_16x16x32_bf16 v[50:53], v[150:153], v[190:193], v[50:53]
	v_mfma_f32_16x16x32_bf16 v[50:53], v[154:157], v[198:201], v[50:53]
	v_mfma_f32_16x16x32_bf16 v[34:37], v[150:153], v[202:205], v[34:37]
	v_mfma_f32_16x16x32_bf16 v[34:37], v[154:157], v[206:209], v[34:37]
	v_mfma_f32_16x16x32_bf16 v[18:21], v[150:153], v[210:213], v[18:21]
	v_mfma_f32_16x16x32_bf16 v[18:21], v[154:157], v[214:217], v[18:21]
	v_mfma_f32_16x16x32_bf16 v[62:65], v[158:161], v[182:185], v[62:65]
	v_mfma_f32_16x16x32_bf16 v[62:65], v[162:165], v[186:189], v[62:65]
	v_mfma_f32_16x16x32_bf16 v[46:49], v[158:161], v[190:193], v[46:49]
	v_mfma_f32_16x16x32_bf16 v[46:49], v[162:165], v[198:201], v[46:49]
	v_mfma_f32_16x16x32_bf16 v[30:33], v[158:161], v[202:205], v[30:33]
	v_mfma_f32_16x16x32_bf16 v[30:33], v[162:165], v[206:209], v[30:33]
	v_mfma_f32_16x16x32_bf16 v[14:17], v[158:161], v[210:213], v[14:17]
	v_mfma_f32_16x16x32_bf16 v[14:17], v[162:165], v[214:217], v[14:17]
	v_mfma_f32_16x16x32_bf16 v[58:61], v[166:169], v[182:185], v[58:61]
	v_mfma_f32_16x16x32_bf16 v[58:61], v[170:173], v[186:189], v[58:61]
	v_mfma_f32_16x16x32_bf16 v[42:45], v[166:169], v[190:193], v[42:45]
	v_mfma_f32_16x16x32_bf16 v[42:45], v[170:173], v[198:201], v[42:45]
	v_mfma_f32_16x16x32_bf16 v[26:29], v[166:169], v[202:205], v[26:29]
	v_mfma_f32_16x16x32_bf16 v[26:29], v[170:173], v[206:209], v[26:29]
	v_mfma_f32_16x16x32_bf16 v[10:13], v[166:169], v[210:213], v[10:13]
	v_mfma_f32_16x16x32_bf16 v[10:13], v[170:173], v[214:217], v[10:13]
	v_mfma_f32_16x16x32_bf16 v[54:57], v[174:177], v[182:185], v[54:57]
	v_mfma_f32_16x16x32_bf16 v[54:57], v[178:181], v[186:189], v[54:57]
	v_mfma_f32_16x16x32_bf16 v[38:41], v[174:177], v[190:193], v[38:41]
	v_mfma_f32_16x16x32_bf16 v[38:41], v[178:181], v[198:201], v[38:41]
	v_mfma_f32_16x16x32_bf16 v[22:25], v[174:177], v[202:205], v[22:25]
	v_mfma_f32_16x16x32_bf16 v[22:25], v[178:181], v[206:209], v[22:25]
	v_mfma_f32_16x16x32_bf16 v[6:9], v[174:177], v[210:213], v[6:9]
	v_mfma_f32_16x16x32_bf16 v[6:9], v[178:181], v[214:217], v[6:9]
	s_setprio 0
	s_barrier
	s_add_i32 s45, s45, 2
	s_add_u32 s10, s10, 0x100
	s_addc_u32 s11, s11, 0
	s_add_u32 s43, s43, 0x100
	s_addc_u32 s44, s44, 0
	s_cmp_gt_u32 s45, 13
	s_cbranch_scc0 .LBB0_154
	s_and_b64 vcc, exec, s[8:9]
	s_cbranch_vccz .LBB0_157
	s_barrier

; #define PG8_STAGE(bufoff, gbase, voff) do { _Pragma("unroll") for (int _i = 0; _i < 2; ++_i) \
;         __builtin_amdgcn_global_load_lds((const unsigned*)((const char*)(gbase) + (voff)[_i]), (PG8_LAS unsigned*)(lds + (bufoff) + ldsw + _i * 8192), 16, 0, 0); } while (0)
; #define PG8_LDA(dst, b, h) do { _Pragma("unroll") for (int m = 0; m < 4; ++m) _Pragma("unroll") for (int k = 0; k < 2; ++k) dst[m][k] = *(const PG8_LAS bf16x8*)(lds + PG8_SA(b, h) + aoff + m * 2048 + k * 1024); } while (0)
; #define PG8_LDB(dst, b, h) do { _Pragma("unroll") for (int n = 0; n < 2; ++n) _Pragma("unroll") for (int k = 0; k < 2; ++k) dst[n][k] = *(const PG8_LAS bf16x8*)(lds + PG8_SB(b, h) + boff + n * 2048 + k * 1024); } while (0)
; #define PG8_MMA(ai, bj, At, Bt) do { __builtin_amdgcn_s_setprio(1); _Pragma("unroll") for (int m = 0; m < 4; ++m) _Pragma("unroll") for (int n = 0; n < 2; ++n) _Pragma("unroll") for (int k = 0; k < 2; ++k) \
;         acc[ai][bj][m][n] = __builtin_amdgcn_mfma_f32_16x16x32_bf16(Bt[n][k], At[m][k], acc[ai][bj][m][n], 0, 0, 0); __builtin_amdgcn_s_setprio(0); } while (0)
; #define PG8_WAIT_V(n) asm volatile("s_waitcnt vmcnt(" #n ")" ::: "memory")
; #define PG8_WAIT_L(n) asm volatile("s_waitcnt lgkmcnt(" #n ")" ::: "memory")
; template <class Epi, class Sched, bool ALIGN_EPI = false, bool SP2 = false>
; __device__ __forceinline__ void gemm_phase(PG8_LAS unsigned char* lds, const Gemm g, const Sched& S, const Epi& E, const int tid_in) {
;     ...
;             const bool last = (t == nt - 2);
;             const char* a1 = cA + (size_t)(t + 1) * kstep;
;             const char* a2 = last ? nA : cA + (size_t)(t + 2) * kstep; const char* b2 = last ? nB : cB + (size_t)(t + 2) * kstep;
;             const char* a3 = a2 + kstep; const char* b3 = b2 + kstep;
;             if (last && has_next) S.a_ready(nxt);
;             if constexpr (SP2) {
;             PG8_LDB(B0, 0, 0); PG8_LDB(B1, 0, 1); PG8_SCHED; PG8_LDA(At, 0, 0); PG8_STAGE(PG8_SA(1, 1), a1 + hstep, voffA);
;             PG8_WAIT_V(8); PG8_WAIT_L(0); PG8_BAR; PG8_MMA(0, 0, At, B0); PG8_MMA(0, 1, At, B1); PG8_BAR; PG8_SCHED;
;             PG8_LDA(At, 0, 1); PG8_STAGE(PG8_SB(0, 0), b2, voffB); PG8_STAGE(PG8_SB(0, 1), b2 + hstep, voffB); PG8_STAGE(PG8_SA(0, 0), a2, voffA);
;             PG8_WAIT_V(8); PG8_WAIT_L(0); PG8_BAR; PG8_MMA(1, 0, At, B0); PG8_MMA(1, 1, At, B1); PG8_BAR; PG8_SCHED;
.LBB0_177:
	s_add_i32 s51, s12, 2
	s_add_u32 s52, s10, 0x80
	s_addc_u32 s13, s11, 0
	s_add_i32 s54, 0, 0x10000
	s_cmp_eq_u32 s31, s12
	s_cselect_b32 s13, s1, s13
	s_cselect_b32 s12, s0, s52
	s_cselect_b32 s53, s45, s15
	s_cselect_b32 s52, s44, s14
	s_add_i32 s55, 0, 0x14000
	v_add_u32_e32 v138, s54, v247
	v_add_u32_e32 v154, s55, v247
	ds_read_b128 v[126:129], v138
	ds_read_b128 v[130:133], v138 offset:1024
	ds_read_b128 v[134:137], v138 offset:2048
	ds_read_b128 v[138:141], v138 offset:3072
	ds_read_b128 v[142:145], v154
	ds_read_b128 v[146:149], v154 offset:1024
	ds_read_b128 v[150:153], v154 offset:2048
	ds_read_b128 v[154:157], v154 offset:3072
	v_lshl_add_u64 v[214:215], s[10:11], 0, v[206:207]
	s_add_i32 m0, s18, 0xc000
	ds_read_b128 v[158:161], v249
	ds_read_b128 v[162:165], v249 offset:1024
	ds_read_b128 v[170:173], v249 offset:2048
	ds_read_b128 v[178:181], v249 offset:3072
	ds_read_b128 v[182:185], v249 offset:4096
	ds_read_b128 v[186:189], v249 offset:5120
	ds_read_b128 v[190:193], v249 offset:6144
	ds_read_b128 v[210:213], v249 offset:7168
	global_load_lds_dwordx4 v[214:215], off
	v_lshl_add_u64 v[214:215], s[10:11], 0, v[208:209]
	s_add_i32 m0, s18, 0xe000
	s_nop 0
	global_load_lds_dwordx4 v[214:215], off
	s_waitcnt vmcnt(8)
	s_waitcnt lgkmcnt(0)
	s_barrier
	s_setprio 1
	s_waitcnt lgkmcnt(0)
	v_mfma_f32_16x16x32_bf16 v[174:177], v[126:129], v[158:161], v[174:177]
	v_mfma_f32_16x16x32_bf16 v[174:177], v[130:133], v[162:165], v[174:177]
	v_mfma_f32_16x16x32_bf16 v[114:117], v[126:129], v[170:173], v[114:117]
	v_mfma_f32_16x16x32_bf16 v[114:117], v[130:133], v[178:181], v[114:117]
	v_mfma_f32_16x16x32_bf16 v[98:101], v[126:129], v[182:185], v[98:101]
	v_mfma_f32_16x16x32_bf16 v[98:101], v[130:133], v[186:189], v[98:101]
	v_mfma_f32_16x16x32_bf16 v[82:85], v[126:129], v[190:193], v[82:85]
	v_mfma_f32_16x16x32_bf16 v[82:85], v[130:133], v[210:213], v[82:85]
	v_mfma_f32_16x16x32_bf16 v[166:169], v[134:137], v[158:161], v[166:169]
	v_mfma_f32_16x16x32_bf16 v[166:169], v[138:141], v[162:165], v[166:169]
	v_mfma_f32_16x16x32_bf16 v[110:113], v[134:137], v[170:173], v[110:113]
	v_mfma_f32_16x16x32_bf16 v[110:113], v[138:141], v[178:181], v[110:113]
	v_mfma_f32_16x16x32_bf16 v[94:97], v[134:137], v[182:185], v[94:97]
	v_mfma_f32_16x16x32_bf16 v[94:97], v[138:141], v[186:189], v[94:97]
	v_mfma_f32_16x16x32_bf16 v[78:81], v[134:137], v[190:193], v[78:81]
	v_mfma_f32_16x16x32_bf16 v[78:81], v[138:141], v[210:213], v[78:81]
	v_mfma_f32_16x16x32_bf16 v[122:125], v[142:145], v[158:161], v[122:125]
	v_mfma_f32_16x16x32_bf16 v[122:125], v[146:149], v[162:165], v[122:125]
	v_mfma_f32_16x16x32_bf16 v[106:109], v[142:145], v[170:173], v[106:109]
	v_mfma_f32_16x16x32_bf16 v[106:109], v[146:149], v[178:181], v[106:109]
	v_mfma_f32_16x16x32_bf16 v[90:93], v[142:145], v[182:185], v[90:93]
	v_mfma_f32_16x16x32_bf16 v[90:93], v[146:149], v[186:189], v[90:93]
	v_mfma_f32_16x16x32_bf16 v[74:77], v[142:145], v[190:193], v[74:77]
	v_mfma_f32_16x16x32_bf16 v[74:77], v[146:149], v[210:213], v[74:77]
	v_mfma_f32_16x16x32_bf16 v[118:121], v[150:153], v[158:161], v[118:121]
	v_mfma_f32_16x16x32_bf16 v[118:121], v[154:157], v[162:165], v[118:121]
	v_mfma_f32_16x16x32_bf16 v[102:105], v[150:153], v[170:173], v[102:105]
	v_mfma_f32_16x16x32_bf16 v[102:105], v[154:157], v[178:181], v[102:105]
	v_mfma_f32_16x16x32_bf16 v[86:89], v[150:153], v[182:185], v[86:89]
	v_mfma_f32_16x16x32_bf16 v[86:89], v[154:157], v[186:189], v[86:89]
	v_mfma_f32_16x16x32_bf16 v[70:73], v[150:153], v[190:193], v[70:73]
	v_mfma_f32_16x16x32_bf16 v[70:73], v[154:157], v[210:213], v[70:73]
	s_setprio 0
	s_barrier
	s_add_i32 s54, s54, s17
	v_lshl_add_u64 v[214:215], s[52:53], 0, v[202:203]
	s_mov_b32 m0, s54
	ds_read_b128 v[158:161], v249 offset:16384
	ds_read_b128 v[162:165], v249 offset:17408
	ds_read_b128 v[170:173], v249 offset:18432
	ds_read_b128 v[178:181], v249 offset:19456
	ds_read_b128 v[182:185], v249 offset:20480
	ds_read_b128 v[186:189], v249 offset:21504
	ds_read_b128 v[190:193], v249 offset:22528
	ds_read_b128 v[210:213], v249 offset:23552
	global_load_lds_dwordx4 v[214:215], off
	s_add_i32 m0, s54, 0x2000
	v_lshl_add_u64 v[216:217], s[52:53], 0, v[198:199]
	s_add_u32 s52, s52, s62
	s_addc_u32 s53, s53, 0
	s_add_i32 s54, s55, s17
	global_load_lds_dwordx4 v[216:217], off
	v_lshl_add_u64 v[218:219], s[52:53], 0, v[202:203]
	s_mov_b32 m0, s54
	v_lshl_add_u64 v[220:221], s[52:53], 0, v[198:199]
	global_load_lds_dwordx4 v[218:219], off
	s_add_i32 m0, s54, 0x2000
	v_lshl_add_u64 v[222:223], s[12:13], 0, v[204:205]
	global_load_lds_dwordx4 v[220:221], off
	s_mov_b32 m0, s18
	v_lshl_add_u64 v[224:225], s[12:13], 0, v[200:201]
	global_load_lds_dwordx4 v[222:223], off
	s_mov_b32 m0, s19
	s_nop 0
	global_load_lds_dwordx4 v[224:225], off
	s_waitcnt vmcnt(8)
	s_waitcnt lgkmcnt(0)
	s_barrier
; #define PG8_STAGE(bufoff, gbase, voff) do { _Pragma("unroll") for (int _i = 0; _i < 2; ++_i) \
;         __builtin_amdgcn_global_load_lds((const unsigned*)((const char*)(gbase) + (voff)[_i]), (PG8_LAS unsigned*)(lds + (bufoff) + ldsw + _i * 8192), 16, 0, 0); } while (0)
; #define PG8_LDA(dst, b, h) do { _Pragma("unroll") for (int m = 0; m < 4; ++m) _Pragma("unroll") for (int k = 0; k < 2; ++k) dst[m][k] = *(const PG8_LAS bf16x8*)(lds + PG8_SA(b, h) + aoff + m * 2048 + k * 1024); } while (0)
; #define PG8_LDB(dst, b, h) do { _Pragma("unroll") for (int n = 0; n < 2; ++n) _Pragma("unroll") for (int k = 0; k < 2; ++k) dst[n][k] = *(const PG8_LAS bf16x8*)(lds + PG8_SB(b, h) + boff + n * 2048 + k * 1024); } while (0)
; #define PG8_MMA(ai, bj, At, Bt) do { __builtin_amdgcn_s_setprio(1); _Pragma("unroll") for (int m = 0; m < 4; ++m) _Pragma("unroll") for (int n = 0; n < 2; ++n) _Pragma("unroll") for (int k = 0; k < 2; ++k) \
;         acc[ai][bj][m][n] = __builtin_amdgcn_mfma_f32_16x16x32_bf16(Bt[n][k], At[m][k], acc[ai][bj][m][n], 0, 0, 0); __builtin_amdgcn_s_setprio(0); } while (0)
; #define PG8_WAIT_V(n) asm volatile("s_waitcnt vmcnt(" #n ")" ::: "memory")
; #define PG8_WAIT_L(n) asm volatile("s_waitcnt lgkmcnt(" #n ")" ::: "memory")
; #define PG8_BAR __builtin_amdgcn_s_barrier()
; #define PG8_SCHED __builtin_amdgcn_sched_barrier(0)
; template <class Epi, class Sched, bool ALIGN_EPI = false, bool SP2 = false>
; __device__ __forceinline__ void gemm_phase(PG8_LAS unsigned char* lds, const Gemm g, const Sched& S, const Epi& E, const int tid_in) {
;     ...
;             PG8_WAIT_V(8); PG8_WAIT_L(0); PG8_BAR; PG8_MMA(1, 0, At, B0); PG8_MMA(1, 1, At, B1); PG8_BAR; PG8_SCHED;
;             PG8_LDB(B0, 1, 0); PG8_LDB(B1, 1, 1); PG8_SCHED; PG8_LDA(At, 1, 0); PG8_STAGE(PG8_SA(0, 1), a2 + hstep, voffA);
;             PG8_WAIT_V(8); PG8_WAIT_L(0); PG8_BAR; PG8_MMA(0, 0, At, B0); PG8_MMA(0, 1, At, B1); PG8_BAR; PG8_SCHED;
	s_setprio 1
	s_waitcnt lgkmcnt(0)
	v_mfma_f32_16x16x32_bf16 v[66:69], v[126:129], v[158:161], v[66:69]
	v_mfma_f32_16x16x32_bf16 v[66:69], v[130:133], v[162:165], v[66:69]
	v_mfma_f32_16x16x32_bf16 v[50:53], v[126:129], v[170:173], v[50:53]
	v_mfma_f32_16x16x32_bf16 v[50:53], v[130:133], v[178:181], v[50:53]
	v_mfma_f32_16x16x32_bf16 v[34:37], v[126:129], v[182:185], v[34:37]
	v_mfma_f32_16x16x32_bf16 v[34:37], v[130:133], v[186:189], v[34:37]
	v_mfma_f32_16x16x32_bf16 v[18:21], v[126:129], v[190:193], v[18:21]
	v_mfma_f32_16x16x32_bf16 v[18:21], v[130:133], v[210:213], v[18:21]
	v_mfma_f32_16x16x32_bf16 v[62:65], v[134:137], v[158:161], v[62:65]
	v_mfma_f32_16x16x32_bf16 v[62:65], v[138:141], v[162:165], v[62:65]
	v_mfma_f32_16x16x32_bf16 v[46:49], v[134:137], v[170:173], v[46:49]
	v_mfma_f32_16x16x32_bf16 v[46:49], v[138:141], v[178:181], v[46:49]
	v_mfma_f32_16x16x32_bf16 v[30:33], v[134:137], v[182:185], v[30:33]
	v_mfma_f32_16x16x32_bf16 v[30:33], v[138:141], v[186:189], v[30:33]
	v_mfma_f32_16x16x32_bf16 v[14:17], v[134:137], v[190:193], v[14:17]
	v_mfma_f32_16x16x32_bf16 v[14:17], v[138:141], v[210:213], v[14:17]
	v_mfma_f32_16x16x32_bf16 v[58:61], v[142:145], v[158:161], v[58:61]
	v_mfma_f32_16x16x32_bf16 v[58:61], v[146:149], v[162:165], v[58:61]
	v_mfma_f32_16x16x32_bf16 v[42:45], v[142:145], v[170:173], v[42:45]
	v_mfma_f32_16x16x32_bf16 v[42:45], v[146:149], v[178:181], v[42:45]
	v_mfma_f32_16x16x32_bf16 v[26:29], v[142:145], v[182:185], v[26:29]
	v_mfma_f32_16x16x32_bf16 v[26:29], v[146:149], v[186:189], v[26:29]
	v_mfma_f32_16x16x32_bf16 v[10:13], v[142:145], v[190:193], v[10:13]
	v_mfma_f32_16x16x32_bf16 v[10:13], v[146:149], v[210:213], v[10:13]
	v_mfma_f32_16x16x32_bf16 v[54:57], v[150:153], v[158:161], v[54:57]
	v_mfma_f32_16x16x32_bf16 v[54:57], v[154:157], v[162:165], v[54:57]
	v_mfma_f32_16x16x32_bf16 v[38:41], v[150:153], v[170:173], v[38:41]
	v_mfma_f32_16x16x32_bf16 v[38:41], v[154:157], v[178:181], v[38:41]
	v_mfma_f32_16x16x32_bf16 v[22:25], v[150:153], v[182:185], v[22:25]
	v_mfma_f32_16x16x32_bf16 v[22:25], v[154:157], v[186:189], v[22:25]
	v_mfma_f32_16x16x32_bf16 v[6:9], v[150:153], v[190:193], v[6:9]
	v_mfma_f32_16x16x32_bf16 v[6:9], v[154:157], v[210:213], v[6:9]
	s_setprio 0
	s_barrier
	s_add_i32 s52, 0, 0x18000
	s_add_i32 s53, 0, 0x1c000
	v_add_u32_e32 v138, s52, v247
	v_add_u32_e32 v154, s53, v247
	ds_read_b128 v[126:129], v138
	ds_read_b128 v[130:133], v138 offset:1024
	ds_read_b128 v[134:137], v138 offset:2048
	ds_read_b128 v[138:141], v138 offset:3072
	ds_read_b128 v[142:145], v154
	ds_read_b128 v[146:149], v154 offset:1024
	ds_read_b128 v[150:153], v154 offset:2048
	ds_read_b128 v[154:157], v154 offset:3072
	s_add_u32 s12, s12, s62
	s_addc_u32 s13, s13, 0
	s_mov_b32 m0, s22
	v_lshl_add_u64 v[226:227], s[12:13], 0, v[204:205]
	ds_read_b128 v[158:161], v249 offset:32768
	ds_read_b128 v[162:165], v249 offset:33792
	ds_read_b128 v[170:173], v249 offset:34816
	ds_read_b128 v[178:181], v249 offset:35840
	ds_read_b128 v[182:185], v249 offset:36864
	ds_read_b128 v[186:189], v249 offset:37888
	ds_read_b128 v[190:193], v249 offset:38912
	ds_read_b128 v[210:213], v249 offset:39936
	global_load_lds_dwordx4 v[226:227], off
	v_lshl_add_u64 v[226:227], s[12:13], 0, v[200:201]
	s_mov_b32 m0, s23
	s_nop 0
	global_load_lds_dwordx4 v[226:227], off
	s_waitcnt vmcnt(8)
	s_waitcnt lgkmcnt(0)
	s_barrier
	s_setprio 1
	s_waitcnt lgkmcnt(0)
	v_mfma_f32_16x16x32_bf16 v[174:177], v[126:129], v[158:161], v[174:177]
	v_mfma_f32_16x16x32_bf16 v[174:177], v[130:133], v[162:165], v[174:177]
	v_mfma_f32_16x16x32_bf16 v[114:117], v[126:129], v[170:173], v[114:117]
	v_mfma_f32_16x16x32_bf16 v[114:117], v[130:133], v[178:181], v[114:117]
	v_mfma_f32_16x16x32_bf16 v[98:101], v[126:129], v[182:185], v[98:101]
	v_mfma_f32_16x16x32_bf16 v[98:101], v[130:133], v[186:189], v[98:101]
	v_mfma_f32_16x16x32_bf16 v[82:85], v[126:129], v[190:193], v[82:85]
	v_mfma_f32_16x16x32_bf16 v[82:85], v[130:133], v[210:213], v[82:85]
	v_mfma_f32_16x16x32_bf16 v[166:169], v[134:137], v[158:161], v[166:169]
	v_mfma_f32_16x16x32_bf16 v[166:169], v[138:141], v[162:165], v[166:169]
	v_mfma_f32_16x16x32_bf16 v[110:113], v[134:137], v[170:173], v[110:113]
	v_mfma_f32_16x16x32_bf16 v[110:113], v[138:141], v[178:181], v[110:113]
	v_mfma_f32_16x16x32_bf16 v[94:97], v[134:137], v[182:185], v[94:97]
	v_mfma_f32_16x16x32_bf16 v[94:97], v[138:141], v[186:189], v[94:97]
	v_mfma_f32_16x16x32_bf16 v[78:81], v[134:137], v[190:193], v[78:81]
	v_mfma_f32_16x16x32_bf16 v[78:81], v[138:141], v[210:213], v[78:81]
	v_mfma_f32_16x16x32_bf16 v[122:125], v[142:145], v[158:161], v[122:125]
	v_mfma_f32_16x16x32_bf16 v[122:125], v[146:149], v[162:165], v[122:125]
	v_mfma_f32_16x16x32_bf16 v[106:109], v[142:145], v[170:173], v[106:109]
	v_mfma_f32_16x16x32_bf16 v[106:109], v[146:149], v[178:181], v[106:109]
	v_mfma_f32_16x16x32_bf16 v[90:93], v[142:145], v[182:185], v[90:93]
	v_mfma_f32_16x16x32_bf16 v[90:93], v[146:149], v[186:189], v[90:93]
	v_mfma_f32_16x16x32_bf16 v[74:77], v[142:145], v[190:193], v[74:77]
	v_mfma_f32_16x16x32_bf16 v[74:77], v[146:149], v[210:213], v[74:77]
	v_mfma_f32_16x16x32_bf16 v[118:121], v[150:153], v[158:161], v[118:121]
	v_mfma_f32_16x16x32_bf16 v[118:121], v[154:157], v[162:165], v[118:121]
	v_mfma_f32_16x16x32_bf16 v[102:105], v[150:153], v[170:173], v[102:105]
	v_mfma_f32_16x16x32_bf16 v[102:105], v[154:157], v[178:181], v[102:105]
	v_mfma_f32_16x16x32_bf16 v[86:89], v[150:153], v[182:185], v[86:89]
	v_mfma_f32_16x16x32_bf16 v[86:89], v[154:157], v[186:189], v[86:89]
	v_mfma_f32_16x16x32_bf16 v[70:73], v[150:153], v[190:193], v[70:73]
	v_mfma_f32_16x16x32_bf16 v[70:73], v[154:157], v[210:213], v[70:73]
	s_setprio 0
	s_barrier
; #define PG8_STAGE(bufoff, gbase, voff) do { _Pragma("unroll") for (int _i = 0; _i < 2; ++_i) \
;         __builtin_amdgcn_global_load_lds((const unsigned*)((const char*)(gbase) + (voff)[_i]), (PG8_LAS unsigned*)(lds + (bufoff) + ldsw + _i * 8192), 16, 0, 0); } while (0)
; #define PG8_LDA(dst, b, h) do { _Pragma("unroll") for (int m = 0; m < 4; ++m) _Pragma("unroll") for (int k = 0; k < 2; ++k) dst[m][k] = *(const PG8_LAS bf16x8*)(lds + PG8_SA(b, h) + aoff + m * 2048 + k * 1024); } while (0)
; #define PG8_MMA(ai, bj, At, Bt) do { __builtin_amdgcn_s_setprio(1); _Pragma("unroll") for (int m = 0; m < 4; ++m) _Pragma("unroll") for (int n = 0; n < 2; ++n) _Pragma("unroll") for (int k = 0; k < 2; ++k) \
;         acc[ai][bj][m][n] = __builtin_amdgcn_mfma_f32_16x16x32_bf16(Bt[n][k], At[m][k], acc[ai][bj][m][n], 0, 0, 0); __builtin_amdgcn_s_setprio(0); } while (0)
; #define PG8_WAIT_V(n) asm volatile("s_waitcnt vmcnt(" #n ")" ::: "memory")
; #define PG8_WAIT_L(n) asm volatile("s_waitcnt lgkmcnt(" #n ")" ::: "memory")
; #define PG8_BAR __builtin_amdgcn_s_barrier()
; #define PG8_SCHED __builtin_amdgcn_sched_barrier(0)
; template <class Epi, class Sched, bool ALIGN_EPI = false, bool SP2 = false>
; __device__ __forceinline__ void gemm_phase(PG8_LAS unsigned char* lds, const Gemm g, const Sched& S, const Epi& E, const int tid_in) {
;     ...
;             PG8_LDA(At, 1, 1); PG8_STAGE(PG8_SB(1, 0), b3, voffB); PG8_STAGE(PG8_SB(1, 1), b3 + hstep, voffB); PG8_STAGE(PG8_SA(1, 0), a3, voffA);
;             PG8_WAIT_V(8); PG8_WAIT_L(0); PG8_BAR; PG8_MMA(1, 0, At, B0); PG8_MMA(1, 1, At, B1); PG8_BAR; PG8_SCHED;
	s_add_i32 s12, s52, s17
	v_lshl_add_u64 v[214:215], v[214:215], 0, s[28:29]
	s_mov_b32 m0, s12
	ds_read_b128 v[158:161], v249 offset:49152
	ds_read_b128 v[162:165], v249 offset:50176
	ds_read_b128 v[170:173], v249 offset:51200
	ds_read_b128 v[178:181], v249 offset:52224
	ds_read_b128 v[182:185], v249 offset:53248
	ds_read_b128 v[186:189], v249 offset:54272
	ds_read_b128 v[190:193], v249 offset:55296
	ds_read_b128 v[210:213], v249 offset:56320
	global_load_lds_dwordx4 v[214:215], off
	v_lshl_add_u64 v[214:215], v[216:217], 0, s[28:29]
	s_add_i32 m0, s12, 0x2000
	s_add_i32 s12, s53, s17
	global_load_lds_dwordx4 v[214:215], off
	v_lshl_add_u64 v[214:215], v[218:219], 0, s[28:29]
	s_mov_b32 m0, s12
	s_nop 0
	global_load_lds_dwordx4 v[214:215], off
	v_lshl_add_u64 v[214:215], v[220:221], 0, s[28:29]
	s_add_i32 m0, s12, 0x2000
	s_nop 0
	global_load_lds_dwordx4 v[214:215], off
	v_lshl_add_u64 v[214:215], v[222:223], 0, s[28:29]
	s_mov_b32 m0, s26
	s_nop 0
	global_load_lds_dwordx4 v[214:215], off
	v_lshl_add_u64 v[214:215], v[224:225], 0, s[28:29]
	s_mov_b32 m0, s27
	s_nop 0
	global_load_lds_dwordx4 v[214:215], off
	s_waitcnt vmcnt(8)
	s_waitcnt lgkmcnt(0)
	s_barrier
	s_setprio 1
	s_waitcnt lgkmcnt(0)
	v_mfma_f32_16x16x32_bf16 v[66:69], v[126:129], v[158:161], v[66:69]
	v_mfma_f32_16x16x32_bf16 v[66:69], v[130:133], v[162:165], v[66:69]
	v_mfma_f32_16x16x32_bf16 v[50:53], v[126:129], v[170:173], v[50:53]
	v_mfma_f32_16x16x32_bf16 v[50:53], v[130:133], v[178:181], v[50:53]
	v_mfma_f32_16x16x32_bf16 v[34:37], v[126:129], v[182:185], v[34:37]
	v_mfma_f32_16x16x32_bf16 v[34:37], v[130:133], v[186:189], v[34:37]
	v_mfma_f32_16x16x32_bf16 v[18:21], v[126:129], v[190:193], v[18:21]
	v_mfma_f32_16x16x32_bf16 v[18:21], v[130:133], v[210:213], v[18:21]
	v_mfma_f32_16x16x32_bf16 v[62:65], v[134:137], v[158:161], v[62:65]
	v_mfma_f32_16x16x32_bf16 v[62:65], v[138:141], v[162:165], v[62:65]
	v_mfma_f32_16x16x32_bf16 v[46:49], v[134:137], v[170:173], v[46:49]
	v_mfma_f32_16x16x32_bf16 v[46:49], v[138:141], v[178:181], v[46:49]
	v_mfma_f32_16x16x32_bf16 v[30:33], v[134:137], v[182:185], v[30:33]
	v_mfma_f32_16x16x32_bf16 v[30:33], v[138:141], v[186:189], v[30:33]
	v_mfma_f32_16x16x32_bf16 v[14:17], v[134:137], v[190:193], v[14:17]
	v_mfma_f32_16x16x32_bf16 v[14:17], v[138:141], v[210:213], v[14:17]
	v_mfma_f32_16x16x32_bf16 v[58:61], v[142:145], v[158:161], v[58:61]
	v_mfma_f32_16x16x32_bf16 v[58:61], v[146:149], v[162:165], v[58:61]
	v_mfma_f32_16x16x32_bf16 v[42:45], v[142:145], v[170:173], v[42:45]
	v_mfma_f32_16x16x32_bf16 v[42:45], v[146:149], v[178:181], v[42:45]
	v_mfma_f32_16x16x32_bf16 v[26:29], v[142:145], v[182:185], v[26:29]
	v_mfma_f32_16x16x32_bf16 v[26:29], v[146:149], v[186:189], v[26:29]
	v_mfma_f32_16x16x32_bf16 v[10:13], v[142:145], v[190:193], v[10:13]
	v_mfma_f32_16x16x32_bf16 v[10:13], v[146:149], v[210:213], v[10:13]
	v_mfma_f32_16x16x32_bf16 v[54:57], v[150:153], v[158:161], v[54:57]
	v_mfma_f32_16x16x32_bf16 v[54:57], v[154:157], v[162:165], v[54:57]
	v_mfma_f32_16x16x32_bf16 v[38:41], v[150:153], v[170:173], v[38:41]
	v_mfma_f32_16x16x32_bf16 v[38:41], v[154:157], v[178:181], v[38:41]
	v_mfma_f32_16x16x32_bf16 v[22:25], v[150:153], v[182:185], v[22:25]
	v_mfma_f32_16x16x32_bf16 v[22:25], v[154:157], v[186:189], v[22:25]
	v_mfma_f32_16x16x32_bf16 v[6:9], v[150:153], v[190:193], v[6:9]
	v_mfma_f32_16x16x32_bf16 v[6:9], v[154:157], v[210:213], v[6:9]
	s_setprio 0
	s_barrier
	s_add_u32 s10, s10, 0x100
	s_addc_u32 s11, s11, 0
	s_add_u32 s14, s14, 0x100
	s_addc_u32 s15, s15, 0
	s_cmp_ge_u32 s51, s30
	s_mov_b32 s12, s51
	s_cbranch_scc0 .LBB0_177
	s_and_b64 vcc, exec, s[42:43]
	s_cbranch_vccz .LBB0_180
	s_barrier
